# merge phase: gate-tile staging de-serialized (8 loads in flight instead of load-wait-store one at a time)
# speedup vs baseline: 1.2697x; 1.0159x over previous
.LBB0_108:
	v_lshrrev_b32_e32 v0, 1, v207
	s_waitcnt vmcnt(7)
	v_and_b32_e32 v130, 15, v206
	s_mov_b32 s2, 0xfffffc0
	v_and_or_b32 v0, v0, s2, v130
	s_movk_i32 s4, 0x110
	s_waitcnt vmcnt(6)
	v_mul_lo_u32 v137, v0, s4
	v_lshrrev_b32_e32 v0, 2, v206
	v_and_b32_e32 v0, 12, v0
	s_waitcnt vmcnt(4)
	v_mov_b32_e32 v143, v163
	v_readlane_b32 s2, v236, 1
	v_and_or_b32 v142, v207, 64, v0
	v_lshlrev_b32_e32 v136, 7, v185
	v_ashrrev_i32_e32 v185, 31, v184
	v_readlane_b32 s3, v236, 2
	v_lshlrev_b32_e32 v0, 4, v143
	v_and_b32_e32 v0, 0xf0, v0
	v_lshl_add_u64 v[130:131], v[184:185], 1, s[2:3]
	v_ashrrev_i32_e32 v134, 4, v143
	v_lshl_add_u64 v[138:139], v[130:131], 0, v[0:1]
	v_add_u32_e32 v132, v134, v136
	v_mad_i64_i32 v[132:133], s[2:3], v132, s93, v[138:139]
	v_mad_u64_u32 v[140:141], s[2:3], v134, s4, v[0:1]
	v_lshl_add_u32 v137, v142, 1, v137
	v_mov_b32_e32 v224, v140
	global_load_dwordx4 v[144:147], v[132:133], off
	v_add_co_u32_e32 v132, vcc, 0x33000, v132
	s_nop 1
	v_addc_co_u32_e32 v133, vcc, 0, v133, vcc
	global_load_dwordx4 v[148:151], v[132:133], off
	v_add_co_u32_e32 v132, vcc, 0x33000, v132
	s_nop 1
	v_addc_co_u32_e32 v133, vcc, 0, v133, vcc
	global_load_dwordx4 v[152:155], v[132:133], off
	v_add_co_u32_e32 v132, vcc, 0x33000, v132
	s_nop 1
	v_addc_co_u32_e32 v133, vcc, 0, v133, vcc
	global_load_dwordx4 v[156:159], v[132:133], off
	v_add_co_u32_e32 v132, vcc, 0x33000, v132
	s_nop 1
	v_addc_co_u32_e32 v133, vcc, 0, v133, vcc
	global_load_dwordx4 v[208:211], v[132:133], off
	v_add_co_u32_e32 v132, vcc, 0x33000, v132
	s_nop 1
	v_addc_co_u32_e32 v133, vcc, 0, v133, vcc
	global_load_dwordx4 v[212:215], v[132:133], off
	v_add_co_u32_e32 v132, vcc, 0x33000, v132
	s_nop 1
	v_addc_co_u32_e32 v133, vcc, 0, v133, vcc
	global_load_dwordx4 v[216:219], v[132:133], off
	v_add_co_u32_e32 v132, vcc, 0x33000, v132
	s_nop 1
	v_addc_co_u32_e32 v133, vcc, 0, v133, vcc
	global_load_dwordx4 v[220:223], v[132:133], off
	s_waitcnt vmcnt(7)
	ds_write_b128 v224, v[144:147]
	s_waitcnt vmcnt(6)
	ds_write_b128 v224, v[148:151] offset:4352
	s_waitcnt vmcnt(5)
	ds_write_b128 v224, v[152:155] offset:8704
	s_waitcnt vmcnt(4)
	ds_write_b128 v224, v[156:159] offset:13056
	s_waitcnt vmcnt(3)
	ds_write_b128 v224, v[208:211] offset:17408
	s_waitcnt vmcnt(2)
	ds_write_b128 v224, v[212:215] offset:21760
	s_waitcnt vmcnt(1)
	ds_write_b128 v224, v[216:219] offset:26112
	s_waitcnt vmcnt(0)
	ds_write_b128 v224, v[220:223] offset:30464
	v_add_u32_e32 v139, 0x2000, v137
	v_add_u32_e32 v140, 0x3000, v137
	s_mov_b32 s4, 3
	s_waitcnt lgkmcnt(0)
	s_barrier
	ds_read2_b64 v[132:135], v137 offset1:4
	v_add_u32_e32 v138, 0x1000, v137
	s_waitcnt lgkmcnt(0)
	v_lshlrev_b32_e32 v0, 16, v132
	v_mul_f32_e32 v0, v94, v0
	v_mul_f32_e32 v94, 0xbfb8aa3b, v126
	v_exp_f32_e32 v94, v94
	s_nop 0
	v_add_f32_e32 v94, 1.0, v94
	v_rcp_f32_e32 v94, v94
	s_nop 0
	v_mul_f32_e32 v0, v94, v0
	v_and_b32_e32 v94, 0xffff0000, v132
	v_mul_f32_e32 v94, v95, v94
	v_mul_f32_e32 v95, 0xbfb8aa3b, v127
	v_exp_f32_e32 v95, v95
	s_nop 0
	v_add_f32_e32 v95, 1.0, v95
	v_rcp_f32_e32 v95, v95
	s_nop 0
	v_mul_f32_e32 v94, v95, v94
	v_cvt_pk_bf16_f32 v126, v0, v94
	v_mul_f32_e32 v94, 0xbfb8aa3b, v128
	v_exp_f32_e32 v94, v94
	v_mul_f32_e32 v95, 0xbfb8aa3b, v129
	v_exp_f32_e32 v95, v95
	v_lshlrev_b32_e32 v0, 16, v133
	v_add_f32_e32 v94, 1.0, v94
	v_rcp_f32_e32 v94, v94
	v_add_f32_e32 v95, 1.0, v95
	v_rcp_f32_e32 v95, v95
	v_mul_f32_e32 v0, v96, v0
	v_mul_f32_e32 v0, v94, v0
	v_and_b32_e32 v94, 0xffff0000, v133
	v_mul_f32_e32 v94, v97, v94
	v_mul_f32_e32 v94, v95, v94
	v_cvt_pk_bf16_f32 v127, v0, v94
	v_lshlrev_b32_e32 v0, 16, v134
	v_mul_f32_e32 v0, v86, v0
	v_mul_f32_e32 v86, 0xbfb8aa3b, v122
	v_exp_f32_e32 v86, v86
	s_nop 0
	v_add_f32_e32 v86, 1.0, v86
	v_rcp_f32_e32 v86, v86
	s_nop 0
	v_mul_f32_e32 v0, v86, v0
	v_and_b32_e32 v86, 0xffff0000, v134
	v_mul_f32_e32 v86, v87, v86
	v_mul_f32_e32 v87, 0xbfb8aa3b, v123
	v_exp_f32_e32 v87, v87
	s_nop 0
	v_add_f32_e32 v87, 1.0, v87
	v_rcp_f32_e32 v87, v87
	s_nop 0
	v_mul_f32_e32 v86, v87, v86
	v_cvt_pk_bf16_f32 v122, v0, v86
	v_mul_f32_e32 v86, 0xbfb8aa3b, v124
	v_exp_f32_e32 v86, v86
	v_mul_f32_e32 v87, 0xbfb8aa3b, v125
	v_exp_f32_e32 v87, v87
	v_lshlrev_b32_e32 v0, 16, v135
	v_add_f32_e32 v86, 1.0, v86
	v_rcp_f32_e32 v86, v86
	v_add_f32_e32 v87, 1.0, v87
	v_rcp_f32_e32 v87, v87
	v_mul_f32_e32 v0, v88, v0
	v_mul_f32_e32 v0, v86, v0
	v_and_b32_e32 v86, 0xffff0000, v135
	v_mul_f32_e32 v86, v89, v86
	v_mul_f32_e32 v86, v87, v86
	v_cvt_pk_bf16_f32 v123, v0, v86
	ds_read2_b64 v[86:89], v137 offset0:8 offset1:12
	s_waitcnt lgkmcnt(0)
	v_lshlrev_b32_e32 v0, 16, v86
	v_mul_f32_e32 v0, v78, v0
	v_mul_f32_e32 v78, 0xbfb8aa3b, v118
	v_exp_f32_e32 v78, v78
	s_nop 0
	v_add_f32_e32 v78, 1.0, v78
	v_rcp_f32_e32 v78, v78
	s_nop 0
	v_mul_f32_e32 v0, v78, v0
	v_and_b32_e32 v78, 0xffff0000, v86
	v_mul_f32_e32 v78, v79, v78
	v_mul_f32_e32 v79, 0xbfb8aa3b, v119
	v_exp_f32_e32 v79, v79
	s_nop 0
	v_add_f32_e32 v79, 1.0, v79
	v_rcp_f32_e32 v79, v79
	s_nop 0
	v_mul_f32_e32 v78, v79, v78
	v_cvt_pk_bf16_f32 v118, v0, v78
	v_mul_f32_e32 v78, 0xbfb8aa3b, v120
	v_exp_f32_e32 v78, v78
	v_mul_f32_e32 v79, 0xbfb8aa3b, v121
	v_exp_f32_e32 v79, v79
	v_lshlrev_b32_e32 v0, 16, v87
	v_add_f32_e32 v78, 1.0, v78
	v_rcp_f32_e32 v78, v78
	v_add_f32_e32 v79, 1.0, v79
	v_rcp_f32_e32 v79, v79
	v_mul_f32_e32 v0, v80, v0
	v_mul_f32_e32 v0, v78, v0
	v_and_b32_e32 v78, 0xffff0000, v87
	v_mul_f32_e32 v78, v81, v78
	v_mul_f32_e32 v78, v79, v78
	v_cvt_pk_bf16_f32 v119, v0, v78
	v_lshlrev_b32_e32 v0, 16, v88
	v_mul_f32_e32 v0, v70, v0
	v_mul_f32_e32 v70, 0xbfb8aa3b, v114
	v_exp_f32_e32 v70, v70
	s_nop 0
	v_add_f32_e32 v70, 1.0, v70
	v_rcp_f32_e32 v70, v70
	s_nop 0
	v_mul_f32_e32 v0, v70, v0
	v_and_b32_e32 v70, 0xffff0000, v88
	v_mul_f32_e32 v70, v71, v70
	v_mul_f32_e32 v71, 0xbfb8aa3b, v115
	v_exp_f32_e32 v71, v71
	s_nop 0
	v_add_f32_e32 v71, 1.0, v71
	v_rcp_f32_e32 v71, v71
	s_nop 0
	v_mul_f32_e32 v70, v71, v70
	v_cvt_pk_bf16_f32 v114, v0, v70
	v_mul_f32_e32 v70, 0xbfb8aa3b, v116
	v_exp_f32_e32 v70, v70
	v_mul_f32_e32 v71, 0xbfb8aa3b, v117
	v_exp_f32_e32 v71, v71
	v_lshlrev_b32_e32 v0, 16, v89
	v_add_f32_e32 v70, 1.0, v70
	v_rcp_f32_e32 v70, v70
	v_add_f32_e32 v71, 1.0, v71
	v_rcp_f32_e32 v71, v71
	v_mul_f32_e32 v0, v72, v0
	v_mul_f32_e32 v0, v70, v0
	v_and_b32_e32 v70, 0xffff0000, v89
	v_mul_f32_e32 v70, v73, v70
	v_mul_f32_e32 v70, v71, v70
	v_cvt_pk_bf16_f32 v115, v0, v70
	ds_read2_b64 v[70:73], v138 offset0:32 offset1:36
	s_waitcnt lgkmcnt(0)
	v_lshlrev_b32_e32 v0, 16, v70
	v_mul_f32_e32 v0, v62, v0
	v_mul_f32_e32 v62, 0xbfb8aa3b, v110
	v_exp_f32_e32 v62, v62
	s_nop 0
	v_add_f32_e32 v62, 1.0, v62
	v_rcp_f32_e32 v62, v62
	s_nop 0
	v_mul_f32_e32 v0, v62, v0
	v_and_b32_e32 v62, 0xffff0000, v70
	v_mul_f32_e32 v62, v63, v62
	v_mul_f32_e32 v63, 0xbfb8aa3b, v111
	v_exp_f32_e32 v63, v63
	s_nop 0
	v_add_f32_e32 v63, 1.0, v63
	v_rcp_f32_e32 v63, v63
	s_nop 0
	v_mul_f32_e32 v62, v63, v62
	v_cvt_pk_bf16_f32 v110, v0, v62
	v_mul_f32_e32 v62, 0xbfb8aa3b, v112
	v_exp_f32_e32 v62, v62
	v_mul_f32_e32 v63, 0xbfb8aa3b, v113
	v_exp_f32_e32 v63, v63
	v_lshlrev_b32_e32 v0, 16, v71
	v_add_f32_e32 v62, 1.0, v62
	v_rcp_f32_e32 v62, v62
	v_add_f32_e32 v63, 1.0, v63
	v_rcp_f32_e32 v63, v63
	v_mul_f32_e32 v0, v64, v0
	v_mul_f32_e32 v0, v62, v0
	v_and_b32_e32 v62, 0xffff0000, v71
	v_mul_f32_e32 v62, v65, v62
	v_mul_f32_e32 v62, v63, v62
	v_cvt_pk_bf16_f32 v111, v0, v62
	v_lshlrev_b32_e32 v0, 16, v72
	v_mul_f32_e32 v0, v54, v0
	v_mul_f32_e32 v54, 0xbfb8aa3b, v106
	v_exp_f32_e32 v54, v54
	s_nop 0
	v_add_f32_e32 v54, 1.0, v54
	v_rcp_f32_e32 v54, v54
	s_nop 0
	v_mul_f32_e32 v0, v54, v0
	v_and_b32_e32 v54, 0xffff0000, v72
	v_mul_f32_e32 v54, v55, v54
	v_mul_f32_e32 v55, 0xbfb8aa3b, v107
	v_exp_f32_e32 v55, v55
	s_nop 0
	v_add_f32_e32 v55, 1.0, v55
	v_rcp_f32_e32 v55, v55
	s_nop 0
	v_mul_f32_e32 v54, v55, v54
	v_cvt_pk_bf16_f32 v106, v0, v54
	v_mul_f32_e32 v54, 0xbfb8aa3b, v108
	v_exp_f32_e32 v54, v54
	v_mul_f32_e32 v55, 0xbfb8aa3b, v109
	v_exp_f32_e32 v55, v55
	v_lshlrev_b32_e32 v0, 16, v73
	v_add_f32_e32 v54, 1.0, v54
	v_rcp_f32_e32 v54, v54
	v_add_f32_e32 v55, 1.0, v55
	v_rcp_f32_e32 v55, v55
	v_mul_f32_e32 v0, v56, v0
	v_mul_f32_e32 v0, v54, v0
	v_and_b32_e32 v54, 0xffff0000, v73
	v_mul_f32_e32 v54, v57, v54
	v_mul_f32_e32 v54, v55, v54
	v_cvt_pk_bf16_f32 v107, v0, v54
	ds_read2_b64 v[54:57], v138 offset0:40 offset1:44
	s_waitcnt lgkmcnt(0)
	v_lshlrev_b32_e32 v0, 16, v54
	v_mul_f32_e32 v0, v46, v0
	v_mul_f32_e32 v46, 0xbfb8aa3b, v102
	v_exp_f32_e32 v46, v46
	s_nop 0
	v_add_f32_e32 v46, 1.0, v46
	v_rcp_f32_e32 v46, v46
	s_nop 0
	v_mul_f32_e32 v0, v46, v0
	v_and_b32_e32 v46, 0xffff0000, v54
	v_mul_f32_e32 v46, v47, v46
	v_mul_f32_e32 v47, 0xbfb8aa3b, v103
	v_exp_f32_e32 v47, v47
	s_nop 0
	v_add_f32_e32 v47, 1.0, v47
	v_rcp_f32_e32 v47, v47
	s_nop 0
	v_mul_f32_e32 v46, v47, v46
	v_cvt_pk_bf16_f32 v102, v0, v46
	v_mul_f32_e32 v46, 0xbfb8aa3b, v104
	v_exp_f32_e32 v46, v46
	v_mul_f32_e32 v47, 0xbfb8aa3b, v105
	v_exp_f32_e32 v47, v47
	v_lshlrev_b32_e32 v0, 16, v55
	v_add_f32_e32 v46, 1.0, v46
	v_rcp_f32_e32 v46, v46
	v_add_f32_e32 v47, 1.0, v47
	v_rcp_f32_e32 v47, v47
	v_mul_f32_e32 v0, v48, v0
	v_mul_f32_e32 v0, v46, v0
	v_and_b32_e32 v46, 0xffff0000, v55
	v_mul_f32_e32 v46, v49, v46
	v_mul_f32_e32 v46, v47, v46
	v_cvt_pk_bf16_f32 v103, v0, v46
	v_lshlrev_b32_e32 v0, 16, v56
	v_mul_f32_e32 v0, v38, v0
	v_mul_f32_e32 v38, 0xbfb8aa3b, v98
	v_exp_f32_e32 v38, v38
	s_nop 0
	v_add_f32_e32 v38, 1.0, v38
	v_rcp_f32_e32 v38, v38
	s_nop 0
	v_mul_f32_e32 v0, v38, v0
	v_and_b32_e32 v38, 0xffff0000, v56
	v_mul_f32_e32 v38, v39, v38
	v_mul_f32_e32 v39, 0xbfb8aa3b, v99
	v_exp_f32_e32 v39, v39
	s_nop 0
	v_add_f32_e32 v39, 1.0, v39
	v_rcp_f32_e32 v39, v39
	s_nop 0
	v_mul_f32_e32 v38, v39, v38
	v_cvt_pk_bf16_f32 v98, v0, v38
	v_mul_f32_e32 v38, 0xbfb8aa3b, v100
	v_exp_f32_e32 v38, v38
	v_mul_f32_e32 v39, 0xbfb8aa3b, v101
	v_exp_f32_e32 v39, v39
	v_lshlrev_b32_e32 v0, 16, v57
	v_add_f32_e32 v38, 1.0, v38
	v_rcp_f32_e32 v38, v38
	v_add_f32_e32 v39, 1.0, v39
	v_rcp_f32_e32 v39, v39
	v_mul_f32_e32 v0, v40, v0
	v_mul_f32_e32 v0, v38, v0
	v_and_b32_e32 v38, 0xffff0000, v57
	v_mul_f32_e32 v38, v41, v38
	v_mul_f32_e32 v38, v39, v38
	v_cvt_pk_bf16_f32 v99, v0, v38
	ds_read2_b64 v[38:41], v139 offset0:64 offset1:68
	s_waitcnt lgkmcnt(0)
	v_lshlrev_b32_e32 v0, 16, v38
	v_mul_f32_e32 v0, v30, v0
	v_mul_f32_e32 v30, 0xbfb8aa3b, v90
	v_exp_f32_e32 v30, v30
	s_nop 0
	v_add_f32_e32 v30, 1.0, v30
	v_rcp_f32_e32 v30, v30
	s_nop 0
	v_mul_f32_e32 v0, v30, v0
	v_and_b32_e32 v30, 0xffff0000, v38
	v_mul_f32_e32 v30, v31, v30
	v_mul_f32_e32 v31, 0xbfb8aa3b, v91
	v_exp_f32_e32 v31, v31
	s_nop 0
	v_add_f32_e32 v31, 1.0, v31
	v_rcp_f32_e32 v31, v31
	s_nop 0
	v_mul_f32_e32 v30, v31, v30
	v_cvt_pk_bf16_f32 v100, v0, v30
	v_mul_f32_e32 v30, 0xbfb8aa3b, v92
	v_exp_f32_e32 v30, v30
	v_mul_f32_e32 v31, 0xbfb8aa3b, v93
	v_exp_f32_e32 v31, v31
	v_lshlrev_b32_e32 v0, 16, v39
	v_add_f32_e32 v30, 1.0, v30
	v_rcp_f32_e32 v30, v30
	v_add_f32_e32 v31, 1.0, v31
	v_rcp_f32_e32 v31, v31
	v_mul_f32_e32 v0, v32, v0
	v_mul_f32_e32 v0, v30, v0
	v_and_b32_e32 v30, 0xffff0000, v39
	v_mul_f32_e32 v30, v33, v30
	v_mul_f32_e32 v30, v31, v30
	v_cvt_pk_bf16_f32 v101, v0, v30
	v_lshlrev_b32_e32 v0, 16, v40
	v_mul_f32_e32 v0, v26, v0
	v_mul_f32_e32 v26, 0xbfb8aa3b, v82
	v_exp_f32_e32 v26, v26
	s_nop 0
	v_add_f32_e32 v26, 1.0, v26
	v_rcp_f32_e32 v26, v26
	s_nop 0
	v_mul_f32_e32 v0, v26, v0
	v_and_b32_e32 v26, 0xffff0000, v40
	v_mul_f32_e32 v26, v27, v26
	v_mul_f32_e32 v27, 0xbfb8aa3b, v83
	v_exp_f32_e32 v27, v27
	s_nop 0
	v_add_f32_e32 v27, 1.0, v27
	v_rcp_f32_e32 v27, v27
	s_nop 0
	v_mul_f32_e32 v26, v27, v26
	v_cvt_pk_bf16_f32 v104, v0, v26
	v_mul_f32_e32 v26, 0xbfb8aa3b, v84
	v_exp_f32_e32 v26, v26
	v_mul_f32_e32 v27, 0xbfb8aa3b, v85
	v_exp_f32_e32 v27, v27
	v_lshlrev_b32_e32 v0, 16, v41
	v_add_f32_e32 v26, 1.0, v26
	v_rcp_f32_e32 v26, v26
	v_add_f32_e32 v27, 1.0, v27
	v_rcp_f32_e32 v27, v27
	v_mul_f32_e32 v0, v28, v0
	v_mul_f32_e32 v0, v26, v0
	v_and_b32_e32 v26, 0xffff0000, v41
	v_mul_f32_e32 v26, v29, v26
	v_mul_f32_e32 v26, v27, v26
	v_cvt_pk_bf16_f32 v105, v0, v26
	ds_read2_b64 v[26:29], v139 offset0:72 offset1:76
	s_waitcnt lgkmcnt(0)
	v_lshlrev_b32_e32 v0, 16, v26
	v_mul_f32_e32 v0, v22, v0
	v_mul_f32_e32 v22, 0xbfb8aa3b, v74
	v_exp_f32_e32 v22, v22
	s_nop 0
	v_add_f32_e32 v22, 1.0, v22
	v_rcp_f32_e32 v22, v22
	s_nop 0
	v_mul_f32_e32 v0, v22, v0
	v_and_b32_e32 v22, 0xffff0000, v26
	v_mul_f32_e32 v22, v23, v22
	v_mul_f32_e32 v23, 0xbfb8aa3b, v75
	v_exp_f32_e32 v23, v23
	s_nop 0
	v_add_f32_e32 v23, 1.0, v23
	v_rcp_f32_e32 v23, v23
	s_nop 0
	v_mul_f32_e32 v22, v23, v22
	v_cvt_pk_bf16_f32 v108, v0, v22
	v_mul_f32_e32 v22, 0xbfb8aa3b, v76
	v_exp_f32_e32 v22, v22
	v_mul_f32_e32 v23, 0xbfb8aa3b, v77
	v_exp_f32_e32 v23, v23
	v_lshlrev_b32_e32 v0, 16, v27
	v_add_f32_e32 v22, 1.0, v22
	v_rcp_f32_e32 v22, v22
	v_add_f32_e32 v23, 1.0, v23
	v_rcp_f32_e32 v23, v23
	v_mul_f32_e32 v0, v24, v0
	v_mul_f32_e32 v0, v22, v0
	v_and_b32_e32 v22, 0xffff0000, v27
	v_mul_f32_e32 v22, v25, v22
	v_mul_f32_e32 v22, v23, v22
	v_cvt_pk_bf16_f32 v109, v0, v22
	v_lshlrev_b32_e32 v0, 16, v28
	v_mul_f32_e32 v0, v18, v0
	v_mul_f32_e32 v18, 0xbfb8aa3b, v66
	v_exp_f32_e32 v18, v18
	s_nop 0
	v_add_f32_e32 v18, 1.0, v18
	v_rcp_f32_e32 v18, v18
	s_nop 0
	v_mul_f32_e32 v0, v18, v0
	v_and_b32_e32 v18, 0xffff0000, v28
	v_mul_f32_e32 v18, v19, v18
	v_mul_f32_e32 v19, 0xbfb8aa3b, v67
	v_exp_f32_e32 v19, v19
	s_nop 0
	v_add_f32_e32 v19, 1.0, v19
	v_rcp_f32_e32 v19, v19
	s_nop 0
	v_mul_f32_e32 v18, v19, v18
	v_cvt_pk_bf16_f32 v112, v0, v18
	v_mul_f32_e32 v18, 0xbfb8aa3b, v68
	v_exp_f32_e32 v18, v18
	v_mul_f32_e32 v19, 0xbfb8aa3b, v69
	v_exp_f32_e32 v19, v19
	v_lshlrev_b32_e32 v0, 16, v29
	v_add_f32_e32 v18, 1.0, v18
	v_rcp_f32_e32 v18, v18
	v_add_f32_e32 v19, 1.0, v19
	v_rcp_f32_e32 v19, v19
	v_mul_f32_e32 v0, v20, v0
	v_mul_f32_e32 v0, v18, v0
	v_and_b32_e32 v18, 0xffff0000, v29
	v_mul_f32_e32 v18, v21, v18
	v_mul_f32_e32 v18, v19, v18
	v_cvt_pk_bf16_f32 v113, v0, v18
	ds_read2_b64 v[18:21], v140 offset0:96 offset1:100
	s_waitcnt lgkmcnt(0)
	v_lshlrev_b32_e32 v0, 16, v18
	v_mul_f32_e32 v0, v14, v0
	v_mul_f32_e32 v14, 0xbfb8aa3b, v58
	v_exp_f32_e32 v14, v14
	s_nop 0
	v_add_f32_e32 v14, 1.0, v14
	v_rcp_f32_e32 v14, v14
	s_nop 0
	v_mul_f32_e32 v0, v14, v0
	v_and_b32_e32 v14, 0xffff0000, v18
	v_mul_f32_e32 v14, v15, v14
	v_mul_f32_e32 v15, 0xbfb8aa3b, v59
	v_exp_f32_e32 v15, v15
	s_nop 0
	v_add_f32_e32 v15, 1.0, v15
	v_rcp_f32_e32 v15, v15
	s_nop 0
	v_mul_f32_e32 v14, v15, v14
	v_cvt_pk_bf16_f32 v116, v0, v14
	v_mul_f32_e32 v14, 0xbfb8aa3b, v60
	v_exp_f32_e32 v14, v14
	v_mul_f32_e32 v15, 0xbfb8aa3b, v61
	v_exp_f32_e32 v15, v15
	v_lshlrev_b32_e32 v0, 16, v19
	v_add_f32_e32 v14, 1.0, v14
	v_rcp_f32_e32 v14, v14
	v_add_f32_e32 v15, 1.0, v15
	v_rcp_f32_e32 v15, v15
	v_mul_f32_e32 v0, v16, v0
	v_mul_f32_e32 v0, v14, v0
	v_and_b32_e32 v14, 0xffff0000, v19
	v_mul_f32_e32 v14, v17, v14
	v_mul_f32_e32 v14, v15, v14
	v_cvt_pk_bf16_f32 v117, v0, v14
	v_lshlrev_b32_e32 v0, 16, v20
	v_mul_f32_e32 v0, v10, v0
	v_mul_f32_e32 v10, 0xbfb8aa3b, v50
	v_exp_f32_e32 v10, v10
	s_nop 0
	v_add_f32_e32 v10, 1.0, v10
	v_rcp_f32_e32 v10, v10
	s_nop 0
	v_mul_f32_e32 v0, v10, v0
	v_and_b32_e32 v10, 0xffff0000, v20
	v_mul_f32_e32 v10, v11, v10
	v_mul_f32_e32 v11, 0xbfb8aa3b, v51
	v_exp_f32_e32 v11, v11
	s_nop 0
	v_add_f32_e32 v11, 1.0, v11
	v_rcp_f32_e32 v11, v11
	s_nop 0
	v_mul_f32_e32 v10, v11, v10
	v_cvt_pk_bf16_f32 v120, v0, v10
	v_mul_f32_e32 v10, 0xbfb8aa3b, v52
	v_exp_f32_e32 v10, v10
	v_mul_f32_e32 v11, 0xbfb8aa3b, v53
	v_exp_f32_e32 v11, v11
	v_lshlrev_b32_e32 v0, 16, v21
	v_add_f32_e32 v10, 1.0, v10
	v_rcp_f32_e32 v10, v10
	v_add_f32_e32 v11, 1.0, v11
	v_rcp_f32_e32 v11, v11
	v_mul_f32_e32 v0, v12, v0
	v_mul_f32_e32 v0, v10, v0
	v_and_b32_e32 v10, 0xffff0000, v21
	v_mul_f32_e32 v10, v13, v10
	v_mul_f32_e32 v10, v11, v10
	v_cvt_pk_bf16_f32 v121, v0, v10
	ds_read2_b64 v[10:13], v140 offset0:104 offset1:108
	s_waitcnt lgkmcnt(0)
	s_barrier
	v_lshlrev_b32_e32 v0, 16, v10
	v_mul_f32_e32 v0, v6, v0
	v_mul_f32_e32 v6, 0xbfb8aa3b, v42
	v_exp_f32_e32 v6, v6
	s_cmp_lt_i32 s4, 2
	v_add_f32_e32 v6, 1.0, v6
	v_rcp_f32_e32 v6, v6
	s_nop 0
	v_mul_f32_e32 v0, v6, v0
	v_and_b32_e32 v6, 0xffff0000, v10
	v_mul_f32_e32 v6, v7, v6
	v_mul_f32_e32 v7, 0xbfb8aa3b, v43
	v_exp_f32_e32 v7, v7
	s_nop 0
	v_add_f32_e32 v7, 1.0, v7
	v_rcp_f32_e32 v7, v7
	s_nop 0
	v_mul_f32_e32 v6, v7, v6
	v_cvt_pk_bf16_f32 v124, v0, v6
	v_mul_f32_e32 v6, 0xbfb8aa3b, v44
	v_exp_f32_e32 v6, v6
	v_mul_f32_e32 v7, 0xbfb8aa3b, v45
	v_exp_f32_e32 v7, v7
	v_lshlrev_b32_e32 v0, 16, v11
	v_add_f32_e32 v6, 1.0, v6
	v_rcp_f32_e32 v6, v6
	v_add_f32_e32 v7, 1.0, v7
	v_rcp_f32_e32 v7, v7
	v_mul_f32_e32 v0, v8, v0
	v_mul_f32_e32 v0, v6, v0
	v_and_b32_e32 v6, 0xffff0000, v11
	v_mul_f32_e32 v6, v9, v6
	v_mul_f32_e32 v6, v7, v6
	v_cvt_pk_bf16_f32 v125, v0, v6
	v_lshlrev_b32_e32 v0, 16, v12
	v_mul_f32_e32 v0, v2, v0
	v_mul_f32_e32 v2, 0xbfb8aa3b, v34
	v_exp_f32_e32 v2, v2
	s_nop 0
	v_add_f32_e32 v2, 1.0, v2
	v_rcp_f32_e32 v2, v2
	s_nop 0
	v_mul_f32_e32 v0, v2, v0
	v_and_b32_e32 v2, 0xffff0000, v12
	v_mul_f32_e32 v2, v3, v2
	v_mul_f32_e32 v3, 0xbfb8aa3b, v35
	v_exp_f32_e32 v3, v3
	s_nop 0
	v_add_f32_e32 v3, 1.0, v3
	v_rcp_f32_e32 v3, v3
	s_nop 0
	v_mul_f32_e32 v2, v3, v2
	v_cvt_pk_bf16_f32 v128, v0, v2
	v_mul_f32_e32 v2, 0xbfb8aa3b, v36
	v_exp_f32_e32 v2, v2
	v_mul_f32_e32 v3, 0xbfb8aa3b, v37
	v_exp_f32_e32 v3, v3
	v_lshlrev_b32_e32 v0, 16, v13
	v_add_f32_e32 v2, 1.0, v2
	v_rcp_f32_e32 v2, v2
	v_add_f32_e32 v3, 1.0, v3
	v_rcp_f32_e32 v3, v3
	v_mul_f32_e32 v0, v4, v0
	v_mul_f32_e32 v0, v2, v0
	v_and_b32_e32 v2, 0xffff0000, v13
	v_mul_f32_e32 v2, v5, v2
	v_mul_f32_e32 v2, v3, v2
	v_cvt_pk_bf16_f32 v129, v0, v2
	s_cbranch_scc1 .LBB0_91
	s_mov_b32 s5, 1
	s_branch .LBB0_112

.LBB0_111:
	s_waitcnt vmcnt(5)
	v_mov_b32_e32 v74, v163
	s_lshl_b32 s40, s5, 10
	v_lshl_add_u64 v[66:67], s[40:41], 1, v[130:131]
	v_lshlrev_b32_e32 v0, 4, v74
	v_and_b32_e32 v0, 0xf0, v0
	v_ashrrev_i32_e32 v68, 4, v74
	v_lshl_add_u64 v[70:71], v[66:67], 0, v[0:1]
	v_add_u32_e32 v66, v68, v136
	v_mad_i64_i32 v[66:67], s[2:3], v66, s93, v[70:71]
	s_movk_i32 s6, 0x110
	v_mad_u64_u32 v[72:73], s[2:3], v68, s6, v[0:1]
	s_add_i32 s5, s5, 1
	s_cmp_eq_u32 s5, s4
	v_mov_b32_e32 v154, v72
	global_load_dwordx4 v[76:79], v[66:67], off
	v_add_co_u32_e32 v66, vcc, 0x33000, v66
	s_nop 1
	v_addc_co_u32_e32 v67, vcc, 0, v67, vcc
	global_load_dwordx4 v[80:83], v[66:67], off
	v_add_co_u32_e32 v66, vcc, 0x33000, v66
	s_nop 1
	v_addc_co_u32_e32 v67, vcc, 0, v67, vcc
	global_load_dwordx4 v[84:87], v[66:67], off
	v_add_co_u32_e32 v66, vcc, 0x33000, v66
	s_nop 1
	v_addc_co_u32_e32 v67, vcc, 0, v67, vcc
	global_load_dwordx4 v[88:91], v[66:67], off
	v_add_co_u32_e32 v66, vcc, 0x33000, v66
	s_nop 1
	v_addc_co_u32_e32 v67, vcc, 0, v67, vcc
	global_load_dwordx4 v[92:95], v[66:67], off
	v_add_co_u32_e32 v66, vcc, 0x33000, v66
	s_nop 1
	v_addc_co_u32_e32 v67, vcc, 0, v67, vcc
	global_load_dwordx4 v[142:145], v[66:67], off
	v_add_co_u32_e32 v66, vcc, 0x33000, v66
	s_nop 1
	v_addc_co_u32_e32 v67, vcc, 0, v67, vcc
	global_load_dwordx4 v[146:149], v[66:67], off
	v_add_co_u32_e32 v66, vcc, 0x33000, v66
	s_nop 1
	v_addc_co_u32_e32 v67, vcc, 0, v67, vcc
	global_load_dwordx4 v[150:153], v[66:67], off
	s_waitcnt vmcnt(7)
	ds_write_b128 v154, v[76:79]
	s_waitcnt vmcnt(6)
	ds_write_b128 v154, v[80:83] offset:4352
	s_waitcnt vmcnt(5)
	ds_write_b128 v154, v[84:87] offset:8704
	s_waitcnt vmcnt(4)
	ds_write_b128 v154, v[88:91] offset:13056
	s_waitcnt vmcnt(3)
	ds_write_b128 v154, v[92:95] offset:17408
	s_waitcnt vmcnt(2)
	ds_write_b128 v154, v[142:145] offset:21760
	s_waitcnt vmcnt(1)
	ds_write_b128 v154, v[146:149] offset:26112
	s_waitcnt vmcnt(0)
	ds_write_b128 v154, v[150:153] offset:30464
	v_lshlrev_b32_e32 v0, 16, v126
	s_waitcnt lgkmcnt(0)
	s_barrier
	ds_read2_b64 v[66:69], v137 offset1:4
	s_waitcnt lgkmcnt(0)
	v_lshlrev_b32_e32 v70, 16, v66
	v_fmac_f32_e32 v0, v62, v70
	v_and_b32_e32 v62, 0xffff0000, v126
	v_and_b32_e32 v66, 0xffff0000, v66
	v_fmac_f32_e32 v62, v63, v66
	v_cvt_pk_bf16_f32 v126, v0, v62
	v_lshlrev_b32_e32 v0, 16, v127
	v_lshlrev_b32_e32 v62, 16, v67
	v_fmac_f32_e32 v0, v64, v62
	v_and_b32_e32 v62, 0xffff0000, v127
	v_and_b32_e32 v63, 0xffff0000, v67
	v_fmac_f32_e32 v62, v65, v63
	v_cvt_pk_bf16_f32 v127, v0, v62
	v_lshlrev_b32_e32 v0, 16, v122
	v_lshlrev_b32_e32 v62, 16, v68
	v_fmac_f32_e32 v0, v58, v62
	v_and_b32_e32 v58, 0xffff0000, v122
	v_and_b32_e32 v62, 0xffff0000, v68
	v_fmac_f32_e32 v58, v59, v62
	v_cvt_pk_bf16_f32 v122, v0, v58
	v_lshlrev_b32_e32 v0, 16, v123
	v_lshlrev_b32_e32 v58, 16, v69
	v_fmac_f32_e32 v0, v60, v58
	v_and_b32_e32 v58, 0xffff0000, v123
	v_and_b32_e32 v59, 0xffff0000, v69
	v_fmac_f32_e32 v58, v61, v59
	v_cvt_pk_bf16_f32 v123, v0, v58
	ds_read2_b64 v[58:61], v137 offset0:8 offset1:12
	v_lshlrev_b32_e32 v0, 16, v118
	s_waitcnt lgkmcnt(0)
	v_lshlrev_b32_e32 v62, 16, v58
	v_fmac_f32_e32 v0, v54, v62
	v_and_b32_e32 v54, 0xffff0000, v118
	v_and_b32_e32 v58, 0xffff0000, v58
	v_fmac_f32_e32 v54, v55, v58
	v_cvt_pk_bf16_f32 v118, v0, v54
	v_lshlrev_b32_e32 v0, 16, v119
	v_lshlrev_b32_e32 v54, 16, v59
	v_fmac_f32_e32 v0, v56, v54
	v_and_b32_e32 v54, 0xffff0000, v119
	v_and_b32_e32 v55, 0xffff0000, v59
	v_fmac_f32_e32 v54, v57, v55
	v_cvt_pk_bf16_f32 v119, v0, v54
	v_lshlrev_b32_e32 v0, 16, v114
	v_lshlrev_b32_e32 v54, 16, v60
	v_fmac_f32_e32 v0, v50, v54
	v_and_b32_e32 v50, 0xffff0000, v114
	v_and_b32_e32 v54, 0xffff0000, v60
	v_fmac_f32_e32 v50, v51, v54
	v_cvt_pk_bf16_f32 v114, v0, v50
	v_lshlrev_b32_e32 v0, 16, v115
	v_lshlrev_b32_e32 v50, 16, v61
	v_fmac_f32_e32 v0, v52, v50
	v_and_b32_e32 v50, 0xffff0000, v115
	v_and_b32_e32 v51, 0xffff0000, v61
	v_fmac_f32_e32 v50, v53, v51
	v_cvt_pk_bf16_f32 v115, v0, v50
	ds_read2_b64 v[50:53], v138 offset0:32 offset1:36
	v_lshlrev_b32_e32 v0, 16, v110
	s_waitcnt lgkmcnt(0)
	v_lshlrev_b32_e32 v54, 16, v50
	v_fmac_f32_e32 v0, v46, v54
	v_and_b32_e32 v46, 0xffff0000, v110
	v_and_b32_e32 v50, 0xffff0000, v50
	v_fmac_f32_e32 v46, v47, v50
	v_cvt_pk_bf16_f32 v110, v0, v46
	v_lshlrev_b32_e32 v0, 16, v111
	v_lshlrev_b32_e32 v46, 16, v51
	v_fmac_f32_e32 v0, v48, v46
	v_and_b32_e32 v46, 0xffff0000, v111
	v_and_b32_e32 v47, 0xffff0000, v51
	v_fmac_f32_e32 v46, v49, v47
	v_cvt_pk_bf16_f32 v111, v0, v46
	v_lshlrev_b32_e32 v0, 16, v106
	v_lshlrev_b32_e32 v46, 16, v52
	v_fmac_f32_e32 v0, v42, v46
	v_and_b32_e32 v42, 0xffff0000, v106
	v_and_b32_e32 v46, 0xffff0000, v52
	v_fmac_f32_e32 v42, v43, v46
	v_cvt_pk_bf16_f32 v106, v0, v42
	v_lshlrev_b32_e32 v0, 16, v107
	v_lshlrev_b32_e32 v42, 16, v53
	v_fmac_f32_e32 v0, v44, v42
	v_and_b32_e32 v42, 0xffff0000, v107
	v_and_b32_e32 v43, 0xffff0000, v53
	v_fmac_f32_e32 v42, v45, v43
	v_cvt_pk_bf16_f32 v107, v0, v42
	ds_read2_b64 v[42:45], v138 offset0:40 offset1:44
	v_lshlrev_b32_e32 v0, 16, v102
	s_waitcnt lgkmcnt(0)
	v_lshlrev_b32_e32 v46, 16, v42
	v_fmac_f32_e32 v0, v38, v46
	v_and_b32_e32 v38, 0xffff0000, v102
	v_and_b32_e32 v42, 0xffff0000, v42
	v_fmac_f32_e32 v38, v39, v42
	v_cvt_pk_bf16_f32 v102, v0, v38
	v_lshlrev_b32_e32 v0, 16, v103
	v_lshlrev_b32_e32 v38, 16, v43
	v_fmac_f32_e32 v0, v40, v38
	v_and_b32_e32 v38, 0xffff0000, v103
	v_and_b32_e32 v39, 0xffff0000, v43
	v_fmac_f32_e32 v38, v41, v39
	v_cvt_pk_bf16_f32 v103, v0, v38
	v_lshlrev_b32_e32 v0, 16, v98
	v_lshlrev_b32_e32 v38, 16, v44
	v_fmac_f32_e32 v0, v34, v38
	v_and_b32_e32 v34, 0xffff0000, v98
	v_and_b32_e32 v38, 0xffff0000, v44
	v_fmac_f32_e32 v34, v35, v38
	v_cvt_pk_bf16_f32 v98, v0, v34
	v_lshlrev_b32_e32 v0, 16, v99
	v_lshlrev_b32_e32 v34, 16, v45
	v_fmac_f32_e32 v0, v36, v34
	v_and_b32_e32 v34, 0xffff0000, v99
	v_and_b32_e32 v35, 0xffff0000, v45
	v_fmac_f32_e32 v34, v37, v35
	v_cvt_pk_bf16_f32 v99, v0, v34
	ds_read2_b64 v[34:37], v139 offset0:64 offset1:68
	v_lshlrev_b32_e32 v0, 16, v100
	s_waitcnt lgkmcnt(0)
	v_lshlrev_b32_e32 v38, 16, v34
	v_fmac_f32_e32 v0, v30, v38
	v_and_b32_e32 v30, 0xffff0000, v100
	v_and_b32_e32 v34, 0xffff0000, v34
	v_fmac_f32_e32 v30, v31, v34
	v_cvt_pk_bf16_f32 v100, v0, v30
	v_lshlrev_b32_e32 v0, 16, v101
	v_lshlrev_b32_e32 v30, 16, v35
	v_fmac_f32_e32 v0, v32, v30
	v_and_b32_e32 v30, 0xffff0000, v101
	v_and_b32_e32 v31, 0xffff0000, v35
	v_fmac_f32_e32 v30, v33, v31
	v_cvt_pk_bf16_f32 v101, v0, v30
	v_lshlrev_b32_e32 v0, 16, v104
	v_lshlrev_b32_e32 v30, 16, v36
	v_fmac_f32_e32 v0, v26, v30
	v_and_b32_e32 v26, 0xffff0000, v104
	v_and_b32_e32 v30, 0xffff0000, v36
	v_fmac_f32_e32 v26, v27, v30
	v_cvt_pk_bf16_f32 v104, v0, v26
	v_lshlrev_b32_e32 v0, 16, v105
	v_lshlrev_b32_e32 v26, 16, v37
	v_fmac_f32_e32 v0, v28, v26
	v_and_b32_e32 v26, 0xffff0000, v105
	v_and_b32_e32 v27, 0xffff0000, v37
	v_fmac_f32_e32 v26, v29, v27
	v_cvt_pk_bf16_f32 v105, v0, v26
	ds_read2_b64 v[26:29], v139 offset0:72 offset1:76
	v_lshlrev_b32_e32 v0, 16, v108
	s_waitcnt lgkmcnt(0)
	v_lshlrev_b32_e32 v30, 16, v26
	v_fmac_f32_e32 v0, v22, v30
	v_and_b32_e32 v22, 0xffff0000, v108
	v_and_b32_e32 v26, 0xffff0000, v26
	v_fmac_f32_e32 v22, v23, v26
	v_cvt_pk_bf16_f32 v108, v0, v22
	v_lshlrev_b32_e32 v0, 16, v109
	v_lshlrev_b32_e32 v22, 16, v27
	v_fmac_f32_e32 v0, v24, v22
	v_and_b32_e32 v22, 0xffff0000, v109
	v_and_b32_e32 v23, 0xffff0000, v27
	v_fmac_f32_e32 v22, v25, v23
	v_cvt_pk_bf16_f32 v109, v0, v22
	v_lshlrev_b32_e32 v0, 16, v112
	v_lshlrev_b32_e32 v22, 16, v28
	v_fmac_f32_e32 v0, v18, v22
	v_and_b32_e32 v18, 0xffff0000, v112
	v_and_b32_e32 v22, 0xffff0000, v28
	v_fmac_f32_e32 v18, v19, v22
	v_cvt_pk_bf16_f32 v112, v0, v18
	v_lshlrev_b32_e32 v0, 16, v113
	v_lshlrev_b32_e32 v18, 16, v29
	v_fmac_f32_e32 v0, v20, v18
	v_and_b32_e32 v18, 0xffff0000, v113
	v_and_b32_e32 v19, 0xffff0000, v29
	v_fmac_f32_e32 v18, v21, v19
	v_cvt_pk_bf16_f32 v113, v0, v18
	ds_read2_b64 v[18:21], v140 offset0:96 offset1:100
	v_lshlrev_b32_e32 v0, 16, v116
	s_waitcnt lgkmcnt(0)
	v_lshlrev_b32_e32 v22, 16, v18
	v_fmac_f32_e32 v0, v14, v22
	v_and_b32_e32 v14, 0xffff0000, v116
	v_and_b32_e32 v18, 0xffff0000, v18
	v_fmac_f32_e32 v14, v15, v18
	v_cvt_pk_bf16_f32 v116, v0, v14
	v_lshlrev_b32_e32 v0, 16, v117
	v_lshlrev_b32_e32 v14, 16, v19
	v_fmac_f32_e32 v0, v16, v14
	v_and_b32_e32 v14, 0xffff0000, v117
	v_and_b32_e32 v15, 0xffff0000, v19
	v_fmac_f32_e32 v14, v17, v15
	v_cvt_pk_bf16_f32 v117, v0, v14
	v_lshlrev_b32_e32 v0, 16, v120
	v_lshlrev_b32_e32 v14, 16, v20
	v_fmac_f32_e32 v0, v10, v14
	v_and_b32_e32 v10, 0xffff0000, v120
	v_and_b32_e32 v14, 0xffff0000, v20
	v_fmac_f32_e32 v10, v11, v14
	v_cvt_pk_bf16_f32 v120, v0, v10
	v_lshlrev_b32_e32 v0, 16, v121
	v_lshlrev_b32_e32 v10, 16, v21
	v_fmac_f32_e32 v0, v12, v10
	v_and_b32_e32 v10, 0xffff0000, v121
	v_and_b32_e32 v11, 0xffff0000, v21
	v_fmac_f32_e32 v10, v13, v11
	v_cvt_pk_bf16_f32 v121, v0, v10
	ds_read2_b64 v[10:13], v140 offset0:104 offset1:108
	v_lshlrev_b32_e32 v0, 16, v124
	s_waitcnt lgkmcnt(0)
	s_barrier
	v_lshlrev_b32_e32 v14, 16, v10
	v_fmac_f32_e32 v0, v6, v14
	v_and_b32_e32 v6, 0xffff0000, v124
	v_and_b32_e32 v10, 0xffff0000, v10
	v_fmac_f32_e32 v6, v7, v10
	v_cvt_pk_bf16_f32 v124, v0, v6
	v_lshlrev_b32_e32 v0, 16, v125
	v_lshlrev_b32_e32 v6, 16, v11
	v_fmac_f32_e32 v0, v8, v6
	v_and_b32_e32 v6, 0xffff0000, v125
	v_and_b32_e32 v7, 0xffff0000, v11
	v_fmac_f32_e32 v6, v9, v7
	v_cvt_pk_bf16_f32 v125, v0, v6
	v_lshlrev_b32_e32 v0, 16, v128
	v_lshlrev_b32_e32 v6, 16, v12
	v_fmac_f32_e32 v0, v2, v6
	v_and_b32_e32 v2, 0xffff0000, v128
	v_and_b32_e32 v6, 0xffff0000, v12
	v_fmac_f32_e32 v2, v3, v6
	v_cvt_pk_bf16_f32 v128, v0, v2
	v_lshlrev_b32_e32 v0, 16, v129
	v_lshlrev_b32_e32 v2, 16, v13
	v_fmac_f32_e32 v0, v4, v2
	v_and_b32_e32 v2, 0xffff0000, v129
	v_and_b32_e32 v3, 0xffff0000, v13
	v_fmac_f32_e32 v2, v5, v3
	v_cvt_pk_bf16_f32 v129, v0, v2
	s_cbranch_scc1 .LBB0_91
